# w_out transposes moved from light workgroups (critical path) to the 64 heavy workgroups' slack, on top of the P0 RMSNorm rewrite
# speedup vs baseline: 1.0275x; 1.0090x over previous
; #define LAS __attribute__((address_space(3)))
; template <bool PERMUTE>
; __device__ __forceinline__ void p0_transpose_item(const float* W, int K, int N, bf16* WT, LAS float* scr, int item, int lane) {
;     const int nblk = N / 32, kb = item / nblk, nb = item % nblk, k0 = 64 * kb, n0 = 32 * nb;
;     float wv[32];
; #pragma unroll
;     for (int i = 0; i < 32; ++i) wv[i] = __builtin_nontemporal_load(W + (size_t)(k0 + 2 * i + (lane >> 5)) * N + n0 + (lane & 31));
; #pragma unroll
;     for (int i = 0; i < 32; ++i) scr[(2 * i + (lane >> 5)) * 33 + (lane & 31)] = wv[i];
; __global__ void __launch_bounds__(NWAVES * 64, 2) fwd_megakernel(Args a) {
;     ...
;                     constexpr int I_OUT = (DMIX / 64) * (DM / 32);
;                     const int it = ((blockIdx.x & 7) * 24 + (l - 8)) * NWAVES + wave;
;                     if (it < I_OUT) p0_transpose_item<false>(a.w_out, DMIX, DM, WOUT, scr, it, lane);
.LBB0_274:
	s_or_b64 exec, exec, s[0:1]
	v_and_b32_e32 v134, 31, v230
	v_lshrrev_b32_e32 v0, 5, v231
	v_lshrrev_b32_e32 v127, 3, v231
	v_lshlrev_b32_e32 v1, 3, v230
	s_barrier
	v_and_b32_e32 v130, 56, v1
	v_mov_b32_e32 v131, 0
	v_mul_u32_u24_e32 v123, 0x90, v127
	v_mul_u32_u24_e32 v125, 0x90, v134
	v_lshlrev_b32_e32 v129, 3, v0
	v_lshlrev_b32_e32 v135, 2, v0
	s_and_b32 s33, s98, 7
	s_lshr_b32 s90, s98, 3
	v_lshrrev_b32_e32 v136, 5, v231
	v_lshlrev_b32_e32 v98, 1, v130
	v_readlane_b32 s1, v253, 29
	s_lshl_b32 s0, s98, 4
	s_nop 2
	s_lshl_b32 s1, s1, 1
	s_add_i32 s0, s0, s1
	s_ashr_i32 s1, s0, 31
	s_lshr_b32 s1, s1, 27
	s_add_i32 s1, s0, s1
	s_and_b32 s2, s1, 0x7ffffe0
	s_sub_i32 s0, s0, s2
	s_lshl_b32 s1, s1, 1
	s_lshl_b32 s0, s0, 5
	s_and_b32 s2, s1, 0xffffffc0
	s_ashr_i32 s1, s0, 31
	v_readlane_b32 s12, v253, 4
	v_or_b32_e32 v2, s2, v136
	s_lshl_b64 s[4:5], s[0:1], 2
	v_readlane_b32 s26, v253, 18
	v_readlane_b32 s27, v253, 19
	s_add_u32 s4, s26, s4
	v_or_b32_e32 v8, 2, v2
	v_or_b32_e32 v10, 4, v2
	v_or_b32_e32 v12, 6, v2
	v_or_b32_e32 v14, 8, v2
	v_or_b32_e32 v16, 10, v2
	v_or_b32_e32 v18, 12, v2
	v_or_b32_e32 v20, 14, v2
	s_addc_u32 s5, s27, s5
	v_lshlrev_b32_e32 v0, 2, v134
	v_mov_b32_e32 v1, 0
	v_ashrrev_i32_e32 v3, 31, v2
	v_ashrrev_i32_e32 v9, 31, v8
	v_ashrrev_i32_e32 v11, 31, v10
	v_ashrrev_i32_e32 v13, 31, v12
	v_ashrrev_i32_e32 v15, 31, v14
	v_ashrrev_i32_e32 v17, 31, v16
	v_ashrrev_i32_e32 v19, 31, v18
	v_ashrrev_i32_e32 v21, 31, v20
	v_lshl_add_u64 v[4:5], s[4:5], 0, v[0:1]
	v_lshlrev_b64 v[6:7], 12, v[2:3]
	v_lshlrev_b64 v[8:9], 12, v[8:9]
	v_lshlrev_b64 v[10:11], 12, v[10:11]
	v_lshlrev_b64 v[12:13], 12, v[12:13]
	v_lshlrev_b64 v[14:15], 12, v[14:15]
	v_lshlrev_b64 v[16:17], 12, v[16:17]
	v_lshlrev_b64 v[18:19], 12, v[18:19]
	v_lshlrev_b64 v[20:21], 12, v[20:21]
	v_lshl_add_u64 v[6:7], v[4:5], 0, v[6:7]
	v_lshl_add_u64 v[8:9], v[4:5], 0, v[8:9]
	v_lshl_add_u64 v[10:11], v[4:5], 0, v[10:11]
	v_lshl_add_u64 v[12:13], v[4:5], 0, v[12:13]
	v_lshl_add_u64 v[14:15], v[4:5], 0, v[14:15]
	v_lshl_add_u64 v[16:17], v[4:5], 0, v[16:17]
	v_lshl_add_u64 v[18:19], v[4:5], 0, v[18:19]
	v_lshl_add_u64 v[20:21], v[4:5], 0, v[20:21]
	global_load_dword v22, v[6:7], off nt
	global_load_dword v23, v[8:9], off nt
	global_load_dword v24, v[10:11], off nt
	global_load_dword v25, v[12:13], off nt
	global_load_dword v26, v[14:15], off nt
	global_load_dword v27, v[16:17], off nt
	global_load_dword v28, v[18:19], off nt
	global_load_dword v29, v[20:21], off nt
	v_or_b32_e32 v6, 16, v2
	v_or_b32_e32 v8, 18, v2
	v_or_b32_e32 v10, 20, v2
	v_or_b32_e32 v12, 22, v2
	v_or_b32_e32 v14, 24, v2
	v_or_b32_e32 v16, 26, v2
	v_or_b32_e32 v18, 28, v2
	v_or_b32_e32 v20, 30, v2
	v_ashrrev_i32_e32 v7, 31, v6
	v_ashrrev_i32_e32 v9, 31, v8
	v_ashrrev_i32_e32 v11, 31, v10
	v_ashrrev_i32_e32 v13, 31, v12
	v_ashrrev_i32_e32 v15, 31, v14
	v_ashrrev_i32_e32 v17, 31, v16
	v_ashrrev_i32_e32 v19, 31, v18
	v_ashrrev_i32_e32 v21, 31, v20
	v_lshlrev_b64 v[6:7], 12, v[6:7]
	v_lshlrev_b64 v[8:9], 12, v[8:9]
	v_lshlrev_b64 v[10:11], 12, v[10:11]
	v_lshlrev_b64 v[12:13], 12, v[12:13]
	v_lshlrev_b64 v[14:15], 12, v[14:15]
	v_lshlrev_b64 v[16:17], 12, v[16:17]
	v_lshlrev_b64 v[18:19], 12, v[18:19]
	v_lshlrev_b64 v[20:21], 12, v[20:21]
	v_lshl_add_u64 v[6:7], v[4:5], 0, v[6:7]
	v_lshl_add_u64 v[8:9], v[4:5], 0, v[8:9]
	v_lshl_add_u64 v[10:11], v[4:5], 0, v[10:11]
	v_lshl_add_u64 v[12:13], v[4:5], 0, v[12:13]
	v_lshl_add_u64 v[14:15], v[4:5], 0, v[14:15]
	v_lshl_add_u64 v[16:17], v[4:5], 0, v[16:17]
	v_lshl_add_u64 v[18:19], v[4:5], 0, v[18:19]
	v_lshl_add_u64 v[20:21], v[4:5], 0, v[20:21]
	global_load_dword v30, v[6:7], off nt
	global_load_dword v31, v[8:9], off nt
	global_load_dword v32, v[10:11], off nt
	global_load_dword v33, v[12:13], off nt
	global_load_dword v34, v[14:15], off nt
	global_load_dword v35, v[16:17], off nt
	global_load_dword v36, v[18:19], off nt
	global_load_dword v37, v[20:21], off nt
	v_or_b32_e32 v6, 32, v2
	v_or_b32_e32 v8, 34, v2
	v_or_b32_e32 v10, 36, v2
	v_or_b32_e32 v12, 38, v2
	v_or_b32_e32 v14, 40, v2
	v_or_b32_e32 v16, 42, v2
	v_or_b32_e32 v18, 44, v2
	v_or_b32_e32 v20, 46, v2
	v_ashrrev_i32_e32 v7, 31, v6
	v_ashrrev_i32_e32 v9, 31, v8
	v_ashrrev_i32_e32 v11, 31, v10
	v_ashrrev_i32_e32 v13, 31, v12
	v_ashrrev_i32_e32 v15, 31, v14
	v_ashrrev_i32_e32 v17, 31, v16
	v_ashrrev_i32_e32 v19, 31, v18
	v_ashrrev_i32_e32 v21, 31, v20
	v_lshlrev_b64 v[6:7], 12, v[6:7]
	v_lshlrev_b64 v[8:9], 12, v[8:9]
	v_lshlrev_b64 v[10:11], 12, v[10:11]
	v_lshlrev_b64 v[12:13], 12, v[12:13]
	v_lshlrev_b64 v[14:15], 12, v[14:15]
	v_lshlrev_b64 v[16:17], 12, v[16:17]
	v_lshlrev_b64 v[18:19], 12, v[18:19]
	v_lshlrev_b64 v[20:21], 12, v[20:21]
	v_lshl_add_u64 v[6:7], v[4:5], 0, v[6:7]
	v_lshl_add_u64 v[8:9], v[4:5], 0, v[8:9]
	v_lshl_add_u64 v[10:11], v[4:5], 0, v[10:11]
	v_lshl_add_u64 v[12:13], v[4:5], 0, v[12:13]
	v_lshl_add_u64 v[14:15], v[4:5], 0, v[14:15]
	v_lshl_add_u64 v[16:17], v[4:5], 0, v[16:17]
	v_lshl_add_u64 v[18:19], v[4:5], 0, v[18:19]
	v_lshl_add_u64 v[20:21], v[4:5], 0, v[20:21]
	global_load_dword v38, v[6:7], off nt
	global_load_dword v39, v[8:9], off nt
	global_load_dword v40, v[10:11], off nt
	global_load_dword v41, v[12:13], off nt
	global_load_dword v42, v[14:15], off nt
	global_load_dword v43, v[16:17], off nt
	global_load_dword v44, v[18:19], off nt
	s_nop 0
	global_load_dword v20, v[20:21], off nt
	v_or_b32_e32 v6, 48, v2
	v_or_b32_e32 v8, 50, v2
	v_or_b32_e32 v10, 52, v2
	v_or_b32_e32 v12, 54, v2
	v_or_b32_e32 v14, 56, v2
	v_or_b32_e32 v16, 58, v2
	v_or_b32_e32 v18, 60, v2
	v_or_b32_e32 v2, 62, v2
	v_ashrrev_i32_e32 v7, 31, v6
	v_ashrrev_i32_e32 v9, 31, v8
	v_ashrrev_i32_e32 v11, 31, v10
	v_ashrrev_i32_e32 v3, 31, v2
	v_lshlrev_b64 v[6:7], 12, v[6:7]
	v_lshlrev_b64 v[8:9], 12, v[8:9]
	v_lshlrev_b64 v[10:11], 12, v[10:11]
	v_ashrrev_i32_e32 v13, 31, v12
	v_ashrrev_i32_e32 v15, 31, v14
	v_ashrrev_i32_e32 v17, 31, v16
	v_ashrrev_i32_e32 v19, 31, v18
	v_lshlrev_b64 v[2:3], 12, v[2:3]
	v_lshl_add_u64 v[6:7], v[4:5], 0, v[6:7]
	v_lshl_add_u64 v[8:9], v[4:5], 0, v[8:9]
	v_lshl_add_u64 v[10:11], v[4:5], 0, v[10:11]
	v_lshlrev_b64 v[12:13], 12, v[12:13]
	v_lshlrev_b64 v[14:15], 12, v[14:15]
	v_lshlrev_b64 v[16:17], 12, v[16:17]
	v_lshlrev_b64 v[18:19], 12, v[18:19]
	v_lshl_add_u64 v[2:3], v[4:5], 0, v[2:3]
	v_lshl_add_u64 v[12:13], v[4:5], 0, v[12:13]
	v_lshl_add_u64 v[14:15], v[4:5], 0, v[14:15]
	v_lshl_add_u64 v[16:17], v[4:5], 0, v[16:17]
	v_lshl_add_u64 v[18:19], v[4:5], 0, v[18:19]
	global_load_dword v4, v[6:7], off nt
	global_load_dword v5, v[8:9], off nt
	s_nop 0
	global_load_dword v6, v[10:11], off nt
	global_load_dword v7, v[12:13], off nt
	global_load_dword v8, v[14:15], off nt
	global_load_dword v9, v[16:17], off nt
	s_nop 0
	global_load_dword v10, v[18:19], off nt
	s_nop 0
	global_load_dword v2, v[2:3], off nt
	v_mul_u32_u24_e32 v3, 0x84, v136
	v_readlane_b32 s1, v253, 30
	s_ashr_i32 s3, s2, 31
	s_lshl_b64 s[2:3], s[2:3], 1
	v_add3_u32 v0, s1, v0, v3
	v_add_u32_e32 v3, 0x400, v0
	s_waitcnt vmcnt(30)
; #define LAS __attribute__((address_space(3)))
; #define LDS_WAIT() asm volatile("s_waitcnt lgkmcnt(0)" ::: "memory")
; __device__ __forceinline__ unsigned pk2(float lo, float hi) { return pg8::cvt_pk_bf16(lo, hi); }
; template <bool PERMUTE>
; __device__ __forceinline__ void p0_transpose_item(const float* W, int K, int N, bf16* WT, LAS float* scr, int item, int lane) {
;     ...
;     for (int i = 0; i < 32; ++i) scr[(2 * i + (lane >> 5)) * 33 + (lane & 31)] = wv[i];
;     LDS_WAIT(); asm volatile("" ::: "memory");
;     const int c = lane & 7;
; #pragma unroll
;     for (int j = 0; j < 4; ++j) { const int n = (lane >> 3) + 8 * j; const LAS float* s = scr + (8 * c) * 33 + n;
;         v4u o; o.x = pk2(s[0 * 33], s[1 * 33]); o.y = pk2(s[2 * 33], s[3 * 33]); o.z = pk2(s[4 * 33], s[5 * 33]); o.w = pk2(s[6 * 33], s[7 * 33]);
;         const int dr = PERMUTE ? win_dst_row(n0 + n) : (n0 + n);
;         if (PERMUTE && n0 < 4096) __builtin_nontemporal_store(o, (v4u*)(WT + (size_t)dr * K + k0 + 8 * c));
;         else *(v4u*)(WT + (size_t)dr * K + k0 + 8 * c) = o; }
	ds_write2_b32 v0, v22, v23 offset1:66
	s_waitcnt vmcnt(28)
	ds_write2_b32 v0, v24, v25 offset0:132 offset1:198
	s_waitcnt vmcnt(26)
	ds_write2_b32 v3, v26, v27 offset0:8 offset1:74
	s_waitcnt vmcnt(24)
	ds_write2_b32 v3, v28, v29 offset0:140 offset1:206
	v_add_u32_e32 v3, 0x800, v0
	s_waitcnt vmcnt(22)
	ds_write2_b32 v3, v30, v31 offset0:16 offset1:82
	s_waitcnt vmcnt(20)
	ds_write2_b32 v3, v32, v33 offset0:148 offset1:214
	v_add_u32_e32 v3, 0xc00, v0
	s_waitcnt vmcnt(18)
	ds_write2_b32 v3, v34, v35 offset0:24 offset1:90
	s_waitcnt vmcnt(16)
	ds_write2_b32 v3, v36, v37 offset0:156 offset1:222
	v_add_u32_e32 v3, 0x1000, v0
	s_waitcnt vmcnt(14)
	ds_write2_b32 v3, v38, v39 offset0:32 offset1:98
	s_waitcnt vmcnt(12)
	ds_write2_b32 v3, v40, v41 offset0:164 offset1:230
	v_add_u32_e32 v3, 0x1400, v0
	s_waitcnt vmcnt(10)
	ds_write2_b32 v3, v42, v43 offset0:40 offset1:106
	s_waitcnt vmcnt(8)
	ds_write2_b32 v3, v44, v20 offset0:172 offset1:238
	v_add_u32_e32 v3, 0x1800, v0
	v_add_u32_e32 v0, 0x1c00, v0
	s_waitcnt vmcnt(6)
	ds_write2_b32 v3, v4, v5 offset0:48 offset1:114
	s_waitcnt vmcnt(4)
	ds_write2_b32 v3, v6, v7 offset0:180 offset1:246
	s_waitcnt vmcnt(2)
	ds_write2_b32 v0, v8, v9 offset0:56 offset1:122
	s_waitcnt vmcnt(0)
	ds_write2_b32 v0, v10, v2 offset0:188 offset1:254
	s_waitcnt lgkmcnt(0)
	v_mul_u32_u24_e32 v0, 0x84, v130
	v_lshlrev_b32_e32 v2, 2, v127
	v_add3_u32 v12, s1, v0, v2
	ds_read2_b32 v[2:3], v12 offset1:33
	s_waitcnt lgkmcnt(0)
	v_cvt_pk_bf16_f32 v2, v2, v3
	ds_read2_b32 v[4:5], v12 offset0:66 offset1:99
	s_waitcnt lgkmcnt(0)
	v_cvt_pk_bf16_f32 v3, v4, v5
	ds_read2_b32 v[4:5], v12 offset0:132 offset1:165
	s_waitcnt lgkmcnt(0)
	v_cvt_pk_bf16_f32 v4, v4, v5
	ds_read2_b32 v[6:7], v12 offset0:198 offset1:231
	v_readlane_b32 s4, v253, 48
	v_readlane_b32 s5, v253, 49
	s_add_u32 s2, s4, s2
	s_waitcnt lgkmcnt(0)
	v_cvt_pk_bf16_f32 v5, v6, v7
	v_or_b32_e32 v6, s0, v127
	s_addc_u32 s3, s5, s3
	v_mov_b32_e32 v99, v1
	v_ashrrev_i32_e32 v7, 31, v6
	v_lshl_add_u64 v[8:9], s[2:3], 0, v[98:99]
	v_lshlrev_b64 v[10:11], 12, v[6:7]
	ds_read2_b32 v[0:1], v12 offset0:8 offset1:41
	v_lshl_add_u64 v[10:11], v[8:9], 0, v[10:11]
	global_store_dwordx4 v[10:11], v[2:5], off
	s_waitcnt lgkmcnt(0)
	v_cvt_pk_bf16_f32 v0, v0, v1
	ds_read2_b32 v[2:3], v12 offset0:74 offset1:107
	s_waitcnt lgkmcnt(0)
	v_cvt_pk_bf16_f32 v1, v2, v3
	ds_read2_b32 v[2:3], v12 offset0:140 offset1:173
	s_waitcnt lgkmcnt(0)
	v_cvt_pk_bf16_f32 v2, v2, v3
	ds_read2_b32 v[4:5], v12 offset0:206 offset1:239
	s_waitcnt lgkmcnt(0)
	v_cvt_pk_bf16_f32 v3, v4, v5
	v_or_b32_e32 v4, 8, v6
	v_ashrrev_i32_e32 v5, 31, v4
	v_lshlrev_b64 v[4:5], 12, v[4:5]
	v_lshl_add_u64 v[4:5], v[8:9], 0, v[4:5]
	ds_read2_b32 v[10:11], v12 offset0:16 offset1:49
	global_store_dwordx4 v[4:5], v[0:3], off
	v_readlane_b32 s13, v253, 5
	v_readlane_b32 s14, v253, 6
	s_waitcnt lgkmcnt(0)
	v_cvt_pk_bf16_f32 v0, v10, v11
	ds_read2_b32 v[2:3], v12 offset0:82 offset1:115
	s_waitcnt lgkmcnt(0)
	v_cvt_pk_bf16_f32 v1, v2, v3
	ds_read2_b32 v[2:3], v12 offset0:148 offset1:181
	s_waitcnt lgkmcnt(0)
	v_cvt_pk_bf16_f32 v2, v2, v3
	ds_read2_b32 v[4:5], v12 offset0:214 offset1:247
	s_waitcnt lgkmcnt(0)
	v_cvt_pk_bf16_f32 v3, v4, v5
	v_or_b32_e32 v4, 16, v6
	v_ashrrev_i32_e32 v5, 31, v4
	v_lshlrev_b64 v[4:5], 12, v[4:5]
	v_lshl_add_u64 v[4:5], v[8:9], 0, v[4:5]
	ds_read2_b32 v[10:11], v12 offset0:24 offset1:57
	global_store_dwordx4 v[4:5], v[0:3], off
	v_readlane_b32 s15, v253, 7
	v_readlane_b32 s16, v253, 8
	s_waitcnt lgkmcnt(0)
	v_cvt_pk_bf16_f32 v0, v10, v11
	ds_read2_b32 v[2:3], v12 offset0:90 offset1:123
	s_waitcnt lgkmcnt(0)
	v_cvt_pk_bf16_f32 v1, v2, v3
	ds_read2_b32 v[2:3], v12 offset0:156 offset1:189
	s_waitcnt lgkmcnt(0)
	v_cvt_pk_bf16_f32 v2, v2, v3
	ds_read2_b32 v[4:5], v12 offset0:222 offset1:255
	s_waitcnt lgkmcnt(0)
	v_cvt_pk_bf16_f32 v3, v4, v5
	v_or_b32_e32 v4, 24, v6
	v_ashrrev_i32_e32 v5, 31, v4
	v_lshlrev_b64 v[4:5], 12, v[4:5]
	v_lshl_add_u64 v[4:5], v[8:9], 0, v[4:5]
	global_store_dwordx4 v[4:5], v[0:3], off
	s_waitcnt lgkmcnt(0)
	v_readlane_b32 s17, v253, 9
	v_readlane_b32 s18, v253, 10
	v_readlane_b32 s19, v253, 11
	v_readlane_b32 s20, v253, 12
	v_readlane_b32 s21, v253, 13
	v_readlane_b32 s22, v253, 14
	v_readlane_b32 s23, v253, 15
	v_readlane_b32 s24, v253, 16
	v_readlane_b32 s25, v253, 17
	v_readlane_b32 s1, v253, 29
	s_lshl_b32 s0, s98, 4
	s_nop 2
	s_lshl_b32 s1, s1, 1
	s_add_i32 s0, s0, s1
	s_add_i32 s0, s0, 1
	s_ashr_i32 s1, s0, 31
	s_lshr_b32 s1, s1, 27
	s_add_i32 s1, s0, s1
	s_and_b32 s2, s1, 0x7ffffe0
	s_sub_i32 s0, s0, s2
	s_lshl_b32 s1, s1, 1
	s_lshl_b32 s0, s0, 5
	s_and_b32 s2, s1, 0xffffffc0
	s_ashr_i32 s1, s0, 31
	v_readlane_b32 s12, v253, 4
	v_or_b32_e32 v2, s2, v136
	s_lshl_b64 s[4:5], s[0:1], 2
	v_readlane_b32 s26, v253, 18
	v_readlane_b32 s27, v253, 19
	s_add_u32 s4, s26, s4
	v_or_b32_e32 v8, 2, v2
	v_or_b32_e32 v10, 4, v2
	v_or_b32_e32 v12, 6, v2
	v_or_b32_e32 v14, 8, v2
	v_or_b32_e32 v16, 10, v2
	v_or_b32_e32 v18, 12, v2
	v_or_b32_e32 v20, 14, v2
	s_addc_u32 s5, s27, s5
	v_lshlrev_b32_e32 v0, 2, v134
	v_mov_b32_e32 v1, 0
	v_ashrrev_i32_e32 v3, 31, v2
	v_ashrrev_i32_e32 v9, 31, v8
	v_ashrrev_i32_e32 v11, 31, v10
	v_ashrrev_i32_e32 v13, 31, v12
	v_ashrrev_i32_e32 v15, 31, v14
	v_ashrrev_i32_e32 v17, 31, v16
	v_ashrrev_i32_e32 v19, 31, v18
	v_ashrrev_i32_e32 v21, 31, v20
	v_lshl_add_u64 v[4:5], s[4:5], 0, v[0:1]
	v_lshlrev_b64 v[6:7], 12, v[2:3]
	v_lshlrev_b64 v[8:9], 12, v[8:9]
	v_lshlrev_b64 v[10:11], 12, v[10:11]
	v_lshlrev_b64 v[12:13], 12, v[12:13]
	v_lshlrev_b64 v[14:15], 12, v[14:15]
	v_lshlrev_b64 v[16:17], 12, v[16:17]
	v_lshlrev_b64 v[18:19], 12, v[18:19]
	v_lshlrev_b64 v[20:21], 12, v[20:21]
; #define LAS __attribute__((address_space(3)))
; template <bool PERMUTE>
; __device__ __forceinline__ void p0_transpose_item(const float* W, int K, int N, bf16* WT, LAS float* scr, int item, int lane) {
;     const int nblk = N / 32, kb = item / nblk, nb = item % nblk, k0 = 64 * kb, n0 = 32 * nb;
;     float wv[32];
; #pragma unroll
;     for (int i = 0; i < 32; ++i) wv[i] = __builtin_nontemporal_load(W + (size_t)(k0 + 2 * i + (lane >> 5)) * N + n0 + (lane & 31));
; #pragma unroll
	v_lshl_add_u64 v[6:7], v[4:5], 0, v[6:7]
	v_lshl_add_u64 v[8:9], v[4:5], 0, v[8:9]
	v_lshl_add_u64 v[10:11], v[4:5], 0, v[10:11]
	v_lshl_add_u64 v[12:13], v[4:5], 0, v[12:13]
	v_lshl_add_u64 v[14:15], v[4:5], 0, v[14:15]
	v_lshl_add_u64 v[16:17], v[4:5], 0, v[16:17]
	v_lshl_add_u64 v[18:19], v[4:5], 0, v[18:19]
	v_lshl_add_u64 v[20:21], v[4:5], 0, v[20:21]
	global_load_dword v22, v[6:7], off nt
	global_load_dword v23, v[8:9], off nt
	global_load_dword v24, v[10:11], off nt
	global_load_dword v25, v[12:13], off nt
	global_load_dword v26, v[14:15], off nt
	global_load_dword v27, v[16:17], off nt
	global_load_dword v28, v[18:19], off nt
	global_load_dword v29, v[20:21], off nt
	v_or_b32_e32 v6, 16, v2
	v_or_b32_e32 v8, 18, v2
	v_or_b32_e32 v10, 20, v2
	v_or_b32_e32 v12, 22, v2
	v_or_b32_e32 v14, 24, v2
	v_or_b32_e32 v16, 26, v2
	v_or_b32_e32 v18, 28, v2
	v_or_b32_e32 v20, 30, v2
	v_ashrrev_i32_e32 v7, 31, v6
	v_ashrrev_i32_e32 v9, 31, v8
	v_ashrrev_i32_e32 v11, 31, v10
	v_ashrrev_i32_e32 v13, 31, v12
	v_ashrrev_i32_e32 v15, 31, v14
	v_ashrrev_i32_e32 v17, 31, v16
	v_ashrrev_i32_e32 v19, 31, v18
	v_ashrrev_i32_e32 v21, 31, v20
	v_lshlrev_b64 v[6:7], 12, v[6:7]
	v_lshlrev_b64 v[8:9], 12, v[8:9]
	v_lshlrev_b64 v[10:11], 12, v[10:11]
	v_lshlrev_b64 v[12:13], 12, v[12:13]
	v_lshlrev_b64 v[14:15], 12, v[14:15]
	v_lshlrev_b64 v[16:17], 12, v[16:17]
	v_lshlrev_b64 v[18:19], 12, v[18:19]
	v_lshlrev_b64 v[20:21], 12, v[20:21]
	v_lshl_add_u64 v[6:7], v[4:5], 0, v[6:7]
	v_lshl_add_u64 v[8:9], v[4:5], 0, v[8:9]
	v_lshl_add_u64 v[10:11], v[4:5], 0, v[10:11]
	v_lshl_add_u64 v[12:13], v[4:5], 0, v[12:13]
	v_lshl_add_u64 v[14:15], v[4:5], 0, v[14:15]
	v_lshl_add_u64 v[16:17], v[4:5], 0, v[16:17]
	v_lshl_add_u64 v[18:19], v[4:5], 0, v[18:19]
	v_lshl_add_u64 v[20:21], v[4:5], 0, v[20:21]
	global_load_dword v30, v[6:7], off nt
	global_load_dword v31, v[8:9], off nt
	global_load_dword v32, v[10:11], off nt
	global_load_dword v33, v[12:13], off nt
	global_load_dword v34, v[14:15], off nt
	global_load_dword v35, v[16:17], off nt
	global_load_dword v36, v[18:19], off nt
	global_load_dword v37, v[20:21], off nt
	v_or_b32_e32 v6, 32, v2
	v_or_b32_e32 v8, 34, v2
	v_or_b32_e32 v10, 36, v2
	v_or_b32_e32 v12, 38, v2
	v_or_b32_e32 v14, 40, v2
	v_or_b32_e32 v16, 42, v2
	v_or_b32_e32 v18, 44, v2
	v_or_b32_e32 v20, 46, v2
	v_ashrrev_i32_e32 v7, 31, v6
	v_ashrrev_i32_e32 v9, 31, v8
	v_ashrrev_i32_e32 v11, 31, v10
	v_ashrrev_i32_e32 v13, 31, v12
	v_ashrrev_i32_e32 v15, 31, v14
	v_ashrrev_i32_e32 v17, 31, v16
	v_ashrrev_i32_e32 v19, 31, v18
	v_ashrrev_i32_e32 v21, 31, v20
	v_lshlrev_b64 v[6:7], 12, v[6:7]
	v_lshlrev_b64 v[8:9], 12, v[8:9]
	v_lshlrev_b64 v[10:11], 12, v[10:11]
	v_lshlrev_b64 v[12:13], 12, v[12:13]
	v_lshlrev_b64 v[14:15], 12, v[14:15]
	v_lshlrev_b64 v[16:17], 12, v[16:17]
	v_lshlrev_b64 v[18:19], 12, v[18:19]
	v_lshlrev_b64 v[20:21], 12, v[20:21]
	v_lshl_add_u64 v[6:7], v[4:5], 0, v[6:7]
	v_lshl_add_u64 v[8:9], v[4:5], 0, v[8:9]
	v_lshl_add_u64 v[10:11], v[4:5], 0, v[10:11]
	v_lshl_add_u64 v[12:13], v[4:5], 0, v[12:13]
	v_lshl_add_u64 v[14:15], v[4:5], 0, v[14:15]
	v_lshl_add_u64 v[16:17], v[4:5], 0, v[16:17]
	v_lshl_add_u64 v[18:19], v[4:5], 0, v[18:19]
	v_lshl_add_u64 v[20:21], v[4:5], 0, v[20:21]
	global_load_dword v38, v[6:7], off nt
	global_load_dword v39, v[8:9], off nt
	global_load_dword v40, v[10:11], off nt
	global_load_dword v41, v[12:13], off nt
	global_load_dword v42, v[14:15], off nt
	global_load_dword v43, v[16:17], off nt
	global_load_dword v44, v[18:19], off nt
	s_nop 0
	global_load_dword v20, v[20:21], off nt
	v_or_b32_e32 v6, 48, v2
	v_or_b32_e32 v8, 50, v2
	v_or_b32_e32 v10, 52, v2
	v_or_b32_e32 v12, 54, v2
	v_or_b32_e32 v14, 56, v2
	v_or_b32_e32 v16, 58, v2
	v_or_b32_e32 v18, 60, v2
	v_or_b32_e32 v2, 62, v2
	v_ashrrev_i32_e32 v7, 31, v6
	v_ashrrev_i32_e32 v9, 31, v8
	v_ashrrev_i32_e32 v11, 31, v10
	v_ashrrev_i32_e32 v3, 31, v2
	v_lshlrev_b64 v[6:7], 12, v[6:7]
	v_lshlrev_b64 v[8:9], 12, v[8:9]
	v_lshlrev_b64 v[10:11], 12, v[10:11]
	v_ashrrev_i32_e32 v13, 31, v12
	v_ashrrev_i32_e32 v15, 31, v14
	v_ashrrev_i32_e32 v17, 31, v16
	v_ashrrev_i32_e32 v19, 31, v18
	v_lshlrev_b64 v[2:3], 12, v[2:3]
	v_lshl_add_u64 v[6:7], v[4:5], 0, v[6:7]
	v_lshl_add_u64 v[8:9], v[4:5], 0, v[8:9]
	v_lshl_add_u64 v[10:11], v[4:5], 0, v[10:11]
	v_lshlrev_b64 v[12:13], 12, v[12:13]
	v_lshlrev_b64 v[14:15], 12, v[14:15]
	v_lshlrev_b64 v[16:17], 12, v[16:17]
	v_lshlrev_b64 v[18:19], 12, v[18:19]
	v_lshl_add_u64 v[2:3], v[4:5], 0, v[2:3]
	v_lshl_add_u64 v[12:13], v[4:5], 0, v[12:13]
	v_lshl_add_u64 v[14:15], v[4:5], 0, v[14:15]
	v_lshl_add_u64 v[16:17], v[4:5], 0, v[16:17]
	v_lshl_add_u64 v[18:19], v[4:5], 0, v[18:19]
	global_load_dword v4, v[6:7], off nt
	global_load_dword v5, v[8:9], off nt
	s_nop 0
	global_load_dword v6, v[10:11], off nt
	global_load_dword v7, v[12:13], off nt
	global_load_dword v8, v[14:15], off nt
	global_load_dword v9, v[16:17], off nt
	s_nop 0
	global_load_dword v10, v[18:19], off nt
	s_nop 0
	global_load_dword v2, v[2:3], off nt
	v_mul_u32_u24_e32 v3, 0x84, v136
	v_readlane_b32 s1, v253, 30
	s_ashr_i32 s3, s2, 31
	s_lshl_b64 s[2:3], s[2:3], 1
	v_add3_u32 v0, s1, v0, v3
	v_add_u32_e32 v3, 0x400, v0
	s_waitcnt vmcnt(30)
; #define LAS __attribute__((address_space(3)))
; #define LDS_WAIT() asm volatile("s_waitcnt lgkmcnt(0)" ::: "memory")
; __device__ __forceinline__ unsigned pk2(float lo, float hi) { return pg8::cvt_pk_bf16(lo, hi); }
; template <bool PERMUTE>
; __device__ __forceinline__ void p0_transpose_item(const float* W, int K, int N, bf16* WT, LAS float* scr, int item, int lane) {
;     ...
;     for (int i = 0; i < 32; ++i) scr[(2 * i + (lane >> 5)) * 33 + (lane & 31)] = wv[i];
;     LDS_WAIT(); asm volatile("" ::: "memory");
;     const int c = lane & 7;
; #pragma unroll
;     for (int j = 0; j < 4; ++j) { const int n = (lane >> 3) + 8 * j; const LAS float* s = scr + (8 * c) * 33 + n;
;         v4u o; o.x = pk2(s[0 * 33], s[1 * 33]); o.y = pk2(s[2 * 33], s[3 * 33]); o.z = pk2(s[4 * 33], s[5 * 33]); o.w = pk2(s[6 * 33], s[7 * 33]);
;         const int dr = PERMUTE ? win_dst_row(n0 + n) : (n0 + n);
;         if (PERMUTE && n0 < 4096) __builtin_nontemporal_store(o, (v4u*)(WT + (size_t)dr * K + k0 + 8 * c));
;         else *(v4u*)(WT + (size_t)dr * K + k0 + 8 * c) = o; }
;     LDS_WAIT(); asm volatile("" ::: "memory");
	ds_write2_b32 v0, v22, v23 offset1:66
	s_waitcnt vmcnt(28)
	ds_write2_b32 v0, v24, v25 offset0:132 offset1:198
	s_waitcnt vmcnt(26)
	ds_write2_b32 v3, v26, v27 offset0:8 offset1:74
	s_waitcnt vmcnt(24)
	ds_write2_b32 v3, v28, v29 offset0:140 offset1:206
	v_add_u32_e32 v3, 0x800, v0
	s_waitcnt vmcnt(22)
	ds_write2_b32 v3, v30, v31 offset0:16 offset1:82
	s_waitcnt vmcnt(20)
	ds_write2_b32 v3, v32, v33 offset0:148 offset1:214
	v_add_u32_e32 v3, 0xc00, v0
	s_waitcnt vmcnt(18)
	ds_write2_b32 v3, v34, v35 offset0:24 offset1:90
	s_waitcnt vmcnt(16)
	ds_write2_b32 v3, v36, v37 offset0:156 offset1:222
	v_add_u32_e32 v3, 0x1000, v0
	s_waitcnt vmcnt(14)
	ds_write2_b32 v3, v38, v39 offset0:32 offset1:98
	s_waitcnt vmcnt(12)
	ds_write2_b32 v3, v40, v41 offset0:164 offset1:230
	v_add_u32_e32 v3, 0x1400, v0
	s_waitcnt vmcnt(10)
	ds_write2_b32 v3, v42, v43 offset0:40 offset1:106
	s_waitcnt vmcnt(8)
	ds_write2_b32 v3, v44, v20 offset0:172 offset1:238
	v_add_u32_e32 v3, 0x1800, v0
	v_add_u32_e32 v0, 0x1c00, v0
	s_waitcnt vmcnt(6)
	ds_write2_b32 v3, v4, v5 offset0:48 offset1:114
	s_waitcnt vmcnt(4)
	ds_write2_b32 v3, v6, v7 offset0:180 offset1:246
	s_waitcnt vmcnt(2)
	ds_write2_b32 v0, v8, v9 offset0:56 offset1:122
	s_waitcnt vmcnt(0)
	ds_write2_b32 v0, v10, v2 offset0:188 offset1:254
	s_waitcnt lgkmcnt(0)
	v_mul_u32_u24_e32 v0, 0x84, v130
	v_lshlrev_b32_e32 v2, 2, v127
	v_add3_u32 v12, s1, v0, v2
	ds_read2_b32 v[2:3], v12 offset1:33
	s_waitcnt lgkmcnt(0)
	v_cvt_pk_bf16_f32 v2, v2, v3
	ds_read2_b32 v[4:5], v12 offset0:66 offset1:99
	s_waitcnt lgkmcnt(0)
	v_cvt_pk_bf16_f32 v3, v4, v5
	ds_read2_b32 v[4:5], v12 offset0:132 offset1:165
	s_waitcnt lgkmcnt(0)
	v_cvt_pk_bf16_f32 v4, v4, v5
	ds_read2_b32 v[6:7], v12 offset0:198 offset1:231
	v_readlane_b32 s4, v253, 48
	v_readlane_b32 s5, v253, 49
	s_add_u32 s2, s4, s2
	s_waitcnt lgkmcnt(0)
	v_cvt_pk_bf16_f32 v5, v6, v7
	v_or_b32_e32 v6, s0, v127
	s_addc_u32 s3, s5, s3
	v_mov_b32_e32 v99, v1
	v_ashrrev_i32_e32 v7, 31, v6
	v_lshl_add_u64 v[8:9], s[2:3], 0, v[98:99]
	v_lshlrev_b64 v[10:11], 12, v[6:7]
	ds_read2_b32 v[0:1], v12 offset0:8 offset1:41
	v_lshl_add_u64 v[10:11], v[8:9], 0, v[10:11]
	global_store_dwordx4 v[10:11], v[2:5], off
	s_waitcnt lgkmcnt(0)
	v_cvt_pk_bf16_f32 v0, v0, v1
	ds_read2_b32 v[2:3], v12 offset0:74 offset1:107
	s_waitcnt lgkmcnt(0)
	v_cvt_pk_bf16_f32 v1, v2, v3
	ds_read2_b32 v[2:3], v12 offset0:140 offset1:173
	s_waitcnt lgkmcnt(0)
	v_cvt_pk_bf16_f32 v2, v2, v3
	ds_read2_b32 v[4:5], v12 offset0:206 offset1:239
	s_waitcnt lgkmcnt(0)
	v_cvt_pk_bf16_f32 v3, v4, v5
	v_or_b32_e32 v4, 8, v6
	v_ashrrev_i32_e32 v5, 31, v4
	v_lshlrev_b64 v[4:5], 12, v[4:5]
	v_lshl_add_u64 v[4:5], v[8:9], 0, v[4:5]
	ds_read2_b32 v[10:11], v12 offset0:16 offset1:49
	global_store_dwordx4 v[4:5], v[0:3], off
	v_readlane_b32 s13, v253, 5
	v_readlane_b32 s14, v253, 6
	s_waitcnt lgkmcnt(0)
	v_cvt_pk_bf16_f32 v0, v10, v11
	ds_read2_b32 v[2:3], v12 offset0:82 offset1:115
	s_waitcnt lgkmcnt(0)
	v_cvt_pk_bf16_f32 v1, v2, v3
	ds_read2_b32 v[2:3], v12 offset0:148 offset1:181
	s_waitcnt lgkmcnt(0)
	v_cvt_pk_bf16_f32 v2, v2, v3
	ds_read2_b32 v[4:5], v12 offset0:214 offset1:247
	s_waitcnt lgkmcnt(0)
	v_cvt_pk_bf16_f32 v3, v4, v5
	v_or_b32_e32 v4, 16, v6
	v_ashrrev_i32_e32 v5, 31, v4
	v_lshlrev_b64 v[4:5], 12, v[4:5]
	v_lshl_add_u64 v[4:5], v[8:9], 0, v[4:5]
	ds_read2_b32 v[10:11], v12 offset0:24 offset1:57
	global_store_dwordx4 v[4:5], v[0:3], off
	v_readlane_b32 s15, v253, 7
	v_readlane_b32 s16, v253, 8
	s_waitcnt lgkmcnt(0)
	v_cvt_pk_bf16_f32 v0, v10, v11
	ds_read2_b32 v[2:3], v12 offset0:90 offset1:123
	s_waitcnt lgkmcnt(0)
	v_cvt_pk_bf16_f32 v1, v2, v3
	ds_read2_b32 v[2:3], v12 offset0:156 offset1:189
	s_waitcnt lgkmcnt(0)
	v_cvt_pk_bf16_f32 v2, v2, v3
	ds_read2_b32 v[4:5], v12 offset0:222 offset1:255
	s_waitcnt lgkmcnt(0)
	v_cvt_pk_bf16_f32 v3, v4, v5
	v_or_b32_e32 v4, 24, v6
	v_ashrrev_i32_e32 v5, 31, v4
	v_lshlrev_b64 v[4:5], 12, v[4:5]
	v_lshl_add_u64 v[4:5], v[8:9], 0, v[4:5]
	global_store_dwordx4 v[4:5], v[0:3], off
	s_waitcnt lgkmcnt(0)
	v_readlane_b32 s17, v253, 9
	v_readlane_b32 s18, v253, 10
	v_readlane_b32 s19, v253, 11
	v_readlane_b32 s20, v253, 12
	v_readlane_b32 s21, v253, 13
	v_readlane_b32 s22, v253, 14
	v_readlane_b32 s23, v253, 15
	v_readlane_b32 s24, v253, 16
	v_readlane_b32 s25, v253, 17
	s_barrier
	s_branch .LBB0_303

; __global__ void __launch_bounds__(NWAVES * 64, 2) fwd_megakernel(Args a) {
;     ...
;                     constexpr int I_OUT = (DMIX / 64) * (DM / 32);
;                     const int it = ((blockIdx.x & 7) * 24 + (l - 8)) * NWAVES + wave;
;                     if (it < I_OUT) p0_transpose_item<false>(a.w_out, DMIX, DM, WOUT, scr, it, lane);
;                     __syncthreads();
.LBB0_300:
	s_or_b64 exec, exec, s[0:1]
	s_mul_i32 s0, s33, 24
	s_add_i32 s0, s90, s0
	s_lshl_b32 s0, s0, 3
	v_readlane_b32 s1, v253, 29
	s_add_i32 s0, s0, s1
	s_sub_i32 s0, s0, 64
	s_cmpk_gt_i32 s0, 0x3ff
	s_barrier
	s_branch .LBB0_302
